# SW attention: per-tile sink values loaded once per unit into lanes of one VGPR and picked with v_readlane; no VMEM load / vmcnt drain inside the tile loop
# speedup vs baseline: 1.0044x; 1.0044x over previous
; __device__ __forceinline__ float shx(float v, int lane, int m) { return __builtin_bit_cast(float, __builtin_amdgcn_ds_bpermute((lane ^ m) << 2, __builtin_bit_cast(int, v))); }
; __device__ __forceinline__ void unpack8(const v4u w, float* v) { v[0] = bf_lo(w.x); v[1] = bf_hi(w.x); v[2] = bf_lo(w.y); v[3] = bf_hi(w.y); v[4] = bf_lo(w.z); v[5] = bf_hi(w.z); v[6] = bf_lo(w.w); v[7] = bf_hi(w.w); }
; __device__ __forceinline__ void sw_attn(const bf16* QKV, const float* rope, const float* qg, const float* kg, const float* sinks, bf16* O, LAS unsigned char* lds, int tid) {
;     ...
;         SW_LOADQ(0);
;         {
;             const int row = tid >> 1, half = tid & 1, kpos = blk * 128 - 128 + row;
;             v4u outw[4];
;             if (kpos >= 0) {
;                 const bf16* kp = QKV + ((size_t)(b * 20 + 16 + kvh) * SEQ + kpos) * 64 + 32 * half;
;                 float v[32];
; #pragma unroll
;                 for (int c = 0; c < 4; ++c) unpack8(*(const v4u*)(kp + 8 * c), v + 8 * c);
;                 float ss = 0.f;
; #pragma unroll
;                 for (int d = 0; d < 32; ++d) ss = fmaf(v[d], v[d], ss);
;                 ss += pg8::shx(ss, lane, 1);
;                 const float rs = __builtin_amdgcn_rsqf(ss * (1.0f / 64.0f) + 1e-6f);
;     ...
;             const float sink = sinks[hq] * 1.4426950408889634f;
.LBB0_159:
	s_bfe_u32 s20, s29, 0x10005
	s_ashr_i32 s10, s29, 6
	s_lshl_b32 s30, s20, 3
	s_mul_i32 s21, s10, 20
	s_ashr_i32 s11, s10, 31
	s_add_i32 s31, s30, s21
	s_and_b32 s16, s29, 31
	s_lshl_b64 s[12:13], s[10:11], 12
	s_add_i32 s10, s31, s28
	s_lshl_b32 s18, s16, 7
	s_ashr_i32 s11, s10, 31
	s_or_b32 s17, s12, s18
	s_lshl_b64 s[10:11], s[10:11], 12
	v_mov_b32_e32 v1, s13
	v_or_b32_e32 v0, s17, v118
	v_mov_b32_e32 v3, s11
	v_or_b32_e32 v2, s10, v118
	v_readlane_b32 s10, v253, 2
	v_or_b32_e32 v2, s18, v2
	v_lshlrev_b64 v[0:1], 6, v[0:1]
	v_readlane_b32 s11, v253, 3
	v_lshlrev_b64 v[2:3], 7, v[2:3]
	s_waitcnt lgkmcnt(0)
	v_lshl_add_u64 v[124:125], s[10:11], 0, v[0:1]
	s_barrier
	v_lshl_add_u64 v[16:17], v[112:113], 0, v[2:3]
	global_load_dwordx4 v[12:15], v[124:125], off offset:48
	global_load_dwordx4 v[8:11], v[124:125], off offset:32
	global_load_dwordx4 v[0:3], v[124:125], off offset:16
	global_load_dwordx4 v[4:7], v[124:125], off
	global_load_dwordx4 v[80:83], v[16:17], off
	global_load_dwordx4 v[84:87], v[16:17], off offset:32
	global_load_dwordx4 v[88:91], v[16:17], off offset:64
	global_load_dwordx4 v[92:95], v[16:17], off offset:96
	s_lshr_b32 s100, s99, 2
	s_add_i32 s100, s100, s30
	s_ashr_i32 s101, s100, 31
	s_lshl_b64 s[100:101], s[100:101], 2
	s_add_u32 s100, s27, s100
	s_addc_u32 s101, s88, s101
	v_mbcnt_lo_u32_b32 v237, -1, 0
	v_mbcnt_hi_u32_b32 v237, -1, v237
	v_and_b32_e32 v237, 3, v237
	v_lshlrev_b32_e32 v237, 3, v237
	global_load_dword v236, v237, s[100:101]
	s_add_i32 s34, s18, 0xffffff80
	v_add_u32_e32 v156, s34, v119
	s_mov_b32 s19, s13
	v_cmp_lt_i32_e32 vcc, -1, v156
	v_mov_b32_e32 v19, 0
	v_mov_b32_e32 v18, 0
	v_mov_b32_e32 v17, 0
	v_mov_b32_e32 v16, 0
	v_mov_b32_e32 v23, 0
	v_mov_b32_e32 v22, 0
	v_mov_b32_e32 v21, 0
	v_mov_b32_e32 v20, 0
	v_mov_b32_e32 v27, 0
	v_mov_b32_e32 v26, 0
	v_mov_b32_e32 v25, 0
	v_mov_b32_e32 v24, 0
	v_mov_b32_e32 v31, 0
	v_mov_b32_e32 v30, 0
	v_mov_b32_e32 v29, 0
	v_mov_b32_e32 v28, 0
	s_and_saveexec_b64 s[10:11], vcc
	s_cbranch_execz .LBB0_163
	s_add_i32 s14, s21, s20
	s_add_i32 s14, s14, 16
	s_ashr_i32 s15, s14, 31
	s_lshl_b64 s[14:15], s[14:15], 19
	s_add_u32 s14, s90, s14
	s_addc_u32 s15, s91, s15
	v_lshlrev_b64 v[16:17], 7, v[156:157]
	v_lshl_add_u64 v[16:17], s[14:15], 0, v[16:17]
	v_mov_b32_e32 v123, v157
	v_lshl_add_u64 v[16:17], v[16:17], 0, v[122:123]
	global_load_dwordx4 v[32:35], v[16:17], off offset:48
	global_load_dwordx4 v[36:39], v[16:17], off offset:32
	global_load_dwordx4 v[56:59], v[16:17], off offset:16
	global_load_dwordx4 v[46:49], v[16:17], off
	ds_read_b128 v[28:31], v129
	ds_read_b128 v[24:27], v129 offset:16
	ds_read_b128 v[20:23], v129 offset:32
	ds_read_b128 v[16:19], v129 offset:48
	s_waitcnt vmcnt(0)
	ds_read_b128 v[62:65], v129 offset:64
	ds_read_b128 v[68:71], v129 offset:80
	s_waitcnt lgkmcnt(4)
	v_mov_b32_e32 v43, v27
	ds_read_b128 v[72:75], v129 offset:96
	s_waitcnt lgkmcnt(3)
	v_mov_b32_e32 v42, v19
	s_waitcnt lgkmcnt(2)
	v_mov_b32_e32 v19, v62
	v_mov_b32_e32 v60, v63
	v_mov_b32_e32 v61, v64
	s_waitcnt lgkmcnt(1)
	v_pk_mov_b32 v[66:67], v[64:65], v[68:69] op_sel:[1,0]
	v_mov_b32_e32 v68, v69
	v_mov_b32_e32 v69, v70
	s_waitcnt vmcnt(3)
	v_lshlrev_b32_e32 v77, 16, v32
	s_waitcnt vmcnt(2)
	v_and_b32_e32 v62, 0xffff0000, v37
	s_waitcnt vmcnt(1)
	v_lshlrev_b32_e32 v44, 16, v56
	s_waitcnt vmcnt(0)
	v_lshlrev_b32_e32 v50, 16, v46
	v_and_b32_e32 v51, 0xffff0000, v46
	v_fma_f32 v27, v50, v50, 0
	v_fmac_f32_e32 v27, v51, v51
	v_lshlrev_b32_e32 v52, 16, v47
	v_and_b32_e32 v53, 0xffff0000, v47
	v_fmac_f32_e32 v27, v52, v52
	v_fmac_f32_e32 v27, v53, v53
	v_lshlrev_b32_e32 v54, 16, v48
	v_and_b32_e32 v55, 0xffff0000, v48
	v_fmac_f32_e32 v27, v54, v54
	v_lshlrev_b32_e32 v102, 16, v49
	v_fmac_f32_e32 v27, v55, v55
	v_and_b32_e32 v41, 0xffff0000, v49
	v_fmac_f32_e32 v27, v102, v102
	v_fmac_f32_e32 v27, v41, v41
	v_and_b32_e32 v45, 0xffff0000, v56
	v_fmac_f32_e32 v27, v44, v44
	v_lshlrev_b32_e32 v46, 16, v57
	v_fmac_f32_e32 v27, v45, v45
	v_and_b32_e32 v47, 0xffff0000, v57
	v_fmac_f32_e32 v27, v46, v46
	v_lshlrev_b32_e32 v48, 16, v58
	v_fmac_f32_e32 v27, v47, v47
	v_and_b32_e32 v49, 0xffff0000, v58
	v_fmac_f32_e32 v27, v48, v48
	v_fmac_f32_e32 v27, v49, v49
	v_lshlrev_b32_e32 v56, 16, v59
	v_and_b32_e32 v40, 0xffff0000, v59
	v_fmac_f32_e32 v27, v56, v56
	v_lshlrev_b32_e32 v57, 16, v36
	v_fmac_f32_e32 v27, v40, v40
	v_fmac_f32_e32 v27, v57, v57
	v_and_b32_e32 v58, 0xffff0000, v36
	v_lshlrev_b32_e32 v59, 16, v37
	v_fmac_f32_e32 v27, v58, v58
	v_fmac_f32_e32 v27, v59, v59
	v_lshlrev_b32_e32 v63, 16, v38
	v_fmac_f32_e32 v27, v62, v62
	v_fmac_f32_e32 v27, v63, v63
	v_and_b32_e32 v64, 0xffff0000, v38
	v_lshlrev_b32_e32 v65, 16, v39
	v_fmac_f32_e32 v27, v64, v64
	v_fmac_f32_e32 v27, v65, v65
	v_and_b32_e32 v76, 0xffff0000, v39
	v_fmac_f32_e32 v27, v76, v76
	ds_read_b128 v[36:39], v129 offset:112
	v_fmac_f32_e32 v27, v77, v77
	v_and_b32_e32 v78, 0xffff0000, v32
	v_lshlrev_b32_e32 v79, 16, v33
	v_fmac_f32_e32 v27, v78, v78
	v_fmac_f32_e32 v27, v79, v79
	v_and_b32_e32 v104, 0xffff0000, v33
	v_lshlrev_b32_e32 v105, 16, v34
	v_fmac_f32_e32 v27, v104, v104
	s_waitcnt lgkmcnt(1)
; __device__ __forceinline__ float shx(float v, int lane, int m) { return __builtin_bit_cast(float, __builtin_amdgcn_ds_bpermute((lane ^ m) << 2, __builtin_bit_cast(int, v))); }
; #define LAS __attribute__((address_space(3)))
; __device__ __forceinline__ void sw_attn(const bf16* QKV, const float* rope, const float* qg, const float* kg, const float* sinks, bf16* O, LAS unsigned char* lds, int tid) {
;     ...
;                 float ss = 0.f;
; #pragma unroll
;                 for (int d = 0; d < 32; ++d) ss = fmaf(v[d], v[d], ss);
;                 ss += pg8::shx(ss, lane, 1);
;                 const float rs = __builtin_amdgcn_rsqf(ss * (1.0f / 64.0f) + 1e-6f);
; #pragma unroll
;                 for (int d4 = 0; d4 < 8; ++d4) { const f32x4 g4 = *(const LAS f32x4*)(gtab + 64 + 32 * half + 4 * d4); v[4 * d4] *= rs * g4[0]; v[4 * d4 + 1] *= rs * g4[1]; v[4 * d4 + 2] *= rs * g4[2]; v[4 * d4 + 3] *= rs * g4[3]; }
;                 if (half == 0) { const f32x4* rp4 = (const f32x4*)(rope + (tok0 + kpos) * 16); const f32x4 c0 = rp4[0], c1 = rp4[1], s0 = rp4[2], s1 = rp4[3];
; #pragma unroll
;                     for (int i = 0; i < 8; ++i) { const float c = i < 4 ? c0[i & 3] : c1[i & 3], sn = i < 4 ? s0[i & 3] : s1[i & 3], x1 = v[i], x2 = v[8 + i]; v[i] = x1 * c - x2 * sn; v[8 + i] = x2 * c + x1 * sn; } }
	v_mov_b32_e32 v99, v74
	v_fmac_f32_e32 v27, v105, v105
	s_waitcnt lgkmcnt(0)
	v_pk_mov_b32 v[106:107], v[74:75], v[36:37] op_sel:[1,0]
	v_and_b32_e32 v74, 0xffff0000, v34
	v_lshlrev_b32_e32 v75, 16, v35
	v_fmac_f32_e32 v27, v74, v74
	v_and_b32_e32 v101, 0xffff0000, v35
	v_fmac_f32_e32 v27, v75, v75
	v_fmac_f32_e32 v27, v101, v101
	ds_bpermute_b32 v32, v121, v27
	v_pk_mov_b32 v[96:97], v[70:71], v[72:73] op_sel:[1,0]
	v_mov_b32_e32 v98, v73
	s_waitcnt lgkmcnt(0)
	v_add_f32_e32 v27, v27, v32
	v_fmamk_f32 v27, v27, 0x3c800000, v232
	v_rsq_f32_e32 v100, v27
	s_nop 0
	v_pk_mul_f32 v[28:29], v[28:29], v[100:101] op_sel_hi:[1,0]
	s_nop 0
	v_pk_mul_f32 v[72:73], v[28:29], v[50:51]
	v_pk_mul_f32 v[28:29], v[30:31], v[100:101] op_sel_hi:[1,0]
	v_pk_mul_f32 v[24:25], v[24:25], v[100:101] op_sel_hi:[1,0]
	v_pk_mul_f32 v[70:71], v[28:29], v[52:53]
	v_pk_mul_f32 v[52:53], v[24:25], v[54:55]
	v_mul_f32_e32 v24, v26, v100
	v_pk_mul_f32 v[26:27], v[42:43], v[100:101] op_sel_hi:[1,0]
	v_pk_mul_f32 v[16:17], v[16:17], v[100:101] op_sel_hi:[1,0]
	v_pk_mul_f32 v[50:51], v[26:27], v[40:41]
	v_pk_mul_f32 v[26:27], v[16:17], v[48:49]
	v_pk_mul_f32 v[16:17], v[18:19], v[100:101] op_sel_hi:[1,0]
	v_pk_mul_f32 v[20:21], v[20:21], v[100:101] op_sel_hi:[1,0]
	v_pk_mul_f32 v[28:29], v[16:17], v[56:57]
	v_pk_mul_f32 v[16:17], v[60:61], v[100:101] op_sel_hi:[1,0]
	v_pk_mul_f32 v[20:21], v[20:21], v[44:45]
	v_pk_mul_f32 v[30:31], v[16:17], v[58:59]
	v_pk_mul_f32 v[16:17], v[66:67], v[100:101] op_sel_hi:[1,0]
	v_pk_mul_f32 v[22:23], v[22:23], v[100:101] op_sel_hi:[1,0]
	v_pk_mul_f32 v[32:33], v[16:17], v[62:63]
	v_pk_mul_f32 v[16:17], v[68:69], v[100:101] op_sel_hi:[1,0]
	v_mul_f32_e32 v24, v24, v102
	v_pk_mul_f32 v[34:35], v[16:17], v[64:65]
	v_pk_mul_f32 v[16:17], v[96:97], v[100:101] op_sel_hi:[1,0]
	v_pk_mul_f32 v[22:23], v[22:23], v[46:47]
	v_pk_mul_f32 v[40:41], v[16:17], v[76:77]
	v_pk_mul_f32 v[16:17], v[98:99], v[100:101] op_sel_hi:[1,0]
	s_nop 0
	v_pk_mul_f32 v[42:43], v[16:17], v[78:79]
	v_pk_mul_f32 v[16:17], v[106:107], v[100:101] op_sel_hi:[1,0]
	s_nop 0
	v_pk_mul_f32 v[44:45], v[16:17], v[104:105]
	v_mov_b32_e32 v16, v37
	v_mov_b32_e32 v17, v38
	v_pk_mul_f32 v[16:17], v[16:17], v[100:101] op_sel_hi:[1,0]
	s_nop 0
	v_pk_mul_f32 v[36:37], v[16:17], v[74:75]
	v_mul_f32_e32 v16, v39, v100
	v_mul_f32_e32 v38, v16, v101
	s_mov_b64 s[14:15], exec
	v_readlane_b32 vcc_lo, v252, 0
	v_readlane_b32 vcc_hi, v252, 1
	s_and_b64 vcc, s[14:15], vcc
	s_mov_b64 exec, vcc
	s_cbranch_execz .LBB0_162
	v_lshl_add_u64 v[16:17], s[12:13], 0, v[156:157]
	v_readlane_b32 s12, v253, 2
	v_lshlrev_b64 v[16:17], 6, v[16:17]
	v_readlane_b32 s13, v253, 3
	v_mov_b32_e32 v25, v51
	s_nop 0
	v_lshl_add_u64 v[58:59], s[12:13], 0, v[16:17]
	global_load_dwordx4 v[16:19], v[58:59], off offset:48
	global_load_dwordx4 v[46:49], v[58:59], off offset:16
	global_load_dwordx4 v[54:57], v[58:59], off offset:32
	s_nop 0
	global_load_dwordx4 v[58:61], v[58:59], off
	s_waitcnt vmcnt(1)
	v_pk_mul_f32 v[62:63], v[20:21], v[54:55]
	v_pk_mul_f32 v[54:55], v[72:73], v[54:55]
	s_waitcnt vmcnt(0)
	v_pk_fma_f32 v[62:63], v[72:73], v[58:59], v[62:63] neg_lo:[0,0,1] neg_hi:[0,0,1]
	v_pk_fma_f32 v[20:21], v[20:21], v[58:59], v[54:55]
	v_pk_mul_f32 v[54:55], v[22:23], v[56:57]
	v_pk_mul_f32 v[56:57], v[70:71], v[56:57]
	v_pk_fma_f32 v[54:55], v[70:71], v[60:61], v[54:55] neg_lo:[0,0,1] neg_hi:[0,0,1]
	v_pk_fma_f32 v[22:23], v[22:23], v[60:61], v[56:57]
	v_pk_mul_f32 v[56:57], v[26:27], v[16:17]
	v_pk_mul_f32 v[16:17], v[52:53], v[16:17]
	v_pk_fma_f32 v[56:57], v[52:53], v[46:47], v[56:57] neg_lo:[0,0,1] neg_hi:[0,0,1]
	v_mov_b32_e32 v52, v28
	v_mov_b32_e32 v53, v50
	v_pk_fma_f32 v[26:27], v[26:27], v[46:47], v[16:17]
	v_mul_f32_e32 v46, v24, v18
	v_pk_mul_f32 v[52:53], v[52:53], v[18:19]
	v_mov_b32_e32 v18, v49
	v_pk_mul_f32 v[18:19], v[50:51], v[18:19]
	v_mul_f32_e32 v16, v28, v48
	v_mov_b32_e32 v17, v18
	v_mov_b32_e32 v47, v19
	v_pk_fma_f32 v[24:25], v[24:25], v[48:49], v[52:53] neg_lo:[0,0,1] neg_hi:[0,0,1]
	v_pk_add_f32 v[16:17], v[16:17], v[46:47]
	v_mov_b32_e32 v72, v62
	v_mov_b32_e32 v73, v63
	v_mov_b32_e32 v70, v54
	v_mov_b32_e32 v71, v55
	v_mov_b32_e32 v52, v56
	v_mov_b32_e32 v53, v57
	v_mov_b32_e32 v51, v25
	v_mov_b32_e32 v28, v16
	v_mov_b32_e32 v50, v17

; #define LAS __attribute__((address_space(3)))
; __device__ __forceinline__ unsigned cvtpk(float lo, float hi) { f32x2_t v = {lo, hi}; bf16x2_t b = __builtin_convertvector(v, bf16x2_t); return __builtin_bit_cast(unsigned, b); }
; __device__ __forceinline__ void unpack8(const v4u w, float* v) { v[0] = bf_lo(w.x); v[1] = bf_hi(w.x); v[2] = bf_lo(w.y); v[3] = bf_hi(w.y); v[4] = bf_lo(w.z); v[5] = bf_hi(w.z); v[6] = bf_lo(w.w); v[7] = bf_hi(w.w); }
; __device__ __forceinline__ void sw_attn(const bf16* QKV, const float* rope, const float* qg, const float* kg, const float* sinks, bf16* O, LAS unsigned char* lds, int tid) {
;     ...
;                 float qv[4][8]; float ss = 0.f;
; #pragma unroll
;                 for (int ks = 0; ks < 4; ++ks) { unpack8(qraw[ks], qv[ks]);
; #pragma unroll
;                     for (int i = 0; i < 8; ++i) ss = fmaf(qv[ks][i], qv[ks][i], ss); }
;                 { float lo_, up_; halves(ss, lo_, up_); ss = lo_ + up_; }
;                 const float rs = __builtin_amdgcn_rsqf(ss * (1.0f / 64.0f) + 1e-6f);
; #pragma unroll
;                 for (int ks = 0; ks < 4; ++ks) { const f32x4 g0 = *(const LAS f32x4*)(gtab + 16 * ks + 8 * hi), g1 = *(const LAS f32x4*)(gtab + 16 * ks + 8 * hi + 4);
; #pragma unroll
;                     for (int i = 0; i < 8; ++i) qv[ks][i] = qv[ks][i] * rs * (i < 4 ? g0[i & 3] : g1[i & 3]); }
; #pragma unroll
;                 for (int i = 0; i < 8; ++i) { float lo_, up_; const float own = qv[0][i]; halves(own, lo_, up_); const float oth = hi ? lo_ : up_, c = i < 4 ? rraw[0][i & 3] : rraw[1][i & 3], sn = i < 4 ? rraw[2][i & 3] : rraw[3][i & 3]; qv[0][i] = own * c + oth * (hi ? sn : -sn); }
; #pragma unroll
;                 for (int ks = 0; ks < 4; ++ks) { const v4u w = {cvtpk(qv[ks][0] * QS, qv[ks][1] * QS), cvtpk(qv[ks][2] * QS, qv[ks][3] * QS), cvtpk(qv[ks][4] * QS, qv[ks][5] * QS), cvtpk(qv[ks][6] * QS, qv[ks][7] * QS)}; qf[ks] = __builtin_bit_cast(bf16x8, w); }
;             }
;             if (p < 3) SW_LOADQ(p + 1);
;             const float sink = sinks[hq] * 1.4426950408889634f;
.LBB0_174:
	v_lshlrev_b32_e32 v30, 16, v80
	v_and_b32_e32 v31, 0xffff0000, v80
	v_fma_f32 v16, v30, v30, 0
	v_lshlrev_b32_e32 v28, 16, v81
	v_fmac_f32_e32 v16, v31, v31
	v_and_b32_e32 v29, 0xffff0000, v81
	v_fmac_f32_e32 v16, v28, v28
	v_lshlrev_b32_e32 v26, 16, v82
	v_fmac_f32_e32 v16, v29, v29
	v_and_b32_e32 v27, 0xffff0000, v82
	v_fmac_f32_e32 v16, v26, v26
	v_lshlrev_b32_e32 v24, 16, v83
	v_fmac_f32_e32 v16, v27, v27
	v_and_b32_e32 v25, 0xffff0000, v83
	v_fmac_f32_e32 v16, v24, v24
	v_lshlrev_b32_e32 v62, 16, v84
	v_fmac_f32_e32 v16, v25, v25
	v_and_b32_e32 v63, 0xffff0000, v84
	v_fmac_f32_e32 v16, v62, v62
	v_lshlrev_b32_e32 v60, 16, v85
	v_fmac_f32_e32 v16, v63, v63
	v_and_b32_e32 v61, 0xffff0000, v85
	v_fmac_f32_e32 v16, v60, v60
	v_lshlrev_b32_e32 v58, 16, v86
	v_fmac_f32_e32 v16, v61, v61
	v_and_b32_e32 v59, 0xffff0000, v86
	v_fmac_f32_e32 v16, v58, v58
	v_lshlrev_b32_e32 v56, 16, v87
	v_fmac_f32_e32 v16, v59, v59
	v_and_b32_e32 v57, 0xffff0000, v87
	v_fmac_f32_e32 v16, v56, v56
	v_lshlrev_b32_e32 v54, 16, v88
	v_fmac_f32_e32 v16, v57, v57
	v_and_b32_e32 v55, 0xffff0000, v88
	v_fmac_f32_e32 v16, v54, v54
	v_lshlrev_b32_e32 v52, 16, v89
	v_fmac_f32_e32 v16, v55, v55
	v_and_b32_e32 v53, 0xffff0000, v89
	v_fmac_f32_e32 v16, v52, v52
	v_lshlrev_b32_e32 v50, 16, v90
	v_fmac_f32_e32 v16, v53, v53
	v_and_b32_e32 v51, 0xffff0000, v90
	v_fmac_f32_e32 v16, v50, v50
	v_lshlrev_b32_e32 v48, 16, v91
	v_fmac_f32_e32 v16, v51, v51
	v_and_b32_e32 v49, 0xffff0000, v91
	v_fmac_f32_e32 v16, v48, v48
	v_lshlrev_b32_e32 v46, 16, v92
	v_fmac_f32_e32 v16, v49, v49
	v_and_b32_e32 v47, 0xffff0000, v92
	v_fmac_f32_e32 v16, v46, v46
	v_lshlrev_b32_e32 v44, 16, v93
	v_fmac_f32_e32 v16, v47, v47
	v_and_b32_e32 v45, 0xffff0000, v93
	v_fmac_f32_e32 v16, v44, v44
	v_lshlrev_b32_e32 v42, 16, v94
	v_fmac_f32_e32 v16, v45, v45
	v_and_b32_e32 v43, 0xffff0000, v94
	v_fmac_f32_e32 v16, v42, v42
	v_lshlrev_b32_e32 v40, 16, v95
	v_fmac_f32_e32 v16, v43, v43
	v_and_b32_e32 v41, 0xffff0000, v95
	v_fmac_f32_e32 v16, v40, v40
	v_fmac_f32_e32 v16, v41, v41
	v_mov_b32_e32 v17, v16
	ds_read_b128 v[20:23], v131 offset:16
	s_nop 0
	v_permlane32_swap_b32_e32 v16, v17
	v_add_f32_e32 v16, v16, v17
	v_fmamk_f32 v16, v16, 0x3c800000, v232
	v_rsq_f32_e32 v68, v16
	ds_read_b128 v[16:19], v131
	s_add_i32 s18, s99, s34
	s_lshr_b32 s101, s34, 3
	s_nop 3
	v_readlane_b32 s100, v236, s101
	s_cmp_eq_u32 s34, 24
	v_pk_mul_f32 v[30:31], v[68:69], v[30:31] op_sel_hi:[0,1]
	s_waitcnt lgkmcnt(0)
	v_pk_mul_f32 v[70:71], v[16:17], v[30:31]
	v_pk_mul_f32 v[16:17], v[68:69], v[28:29] op_sel_hi:[0,1]
	v_pk_mul_f32 v[72:73], v[18:19], v[16:17]
	v_pk_mul_f32 v[16:17], v[68:69], v[26:27] op_sel_hi:[0,1]
	v_pk_mul_f32 v[64:65], v[20:21], v[16:17]
	v_pk_mul_f32 v[16:17], v[68:69], v[24:25] op_sel_hi:[0,1]
	v_pk_mul_f32 v[66:67], v[22:23], v[16:17]
	ds_read_b128 v[36:39], v131 offset:64
	ds_read_b128 v[32:35], v131 offset:80
	ds_read_b128 v[28:31], v131 offset:128
	ds_read_b128 v[24:27], v131 offset:144
	ds_read_b128 v[20:23], v131 offset:192
	ds_read_b128 v[16:19], v131 offset:208
	v_mov_b32_e32 v74, v70
	v_mov_b32_e32 v76, v71
	v_mov_b32_e32 v77, v72
	v_mov_b32_e32 v123, v73
	v_mov_b32_e32 v144, v64
	v_mov_b32_e32 v147, v65
	v_mov_b32_e32 v148, v66
	v_mov_b32_e32 v151, v67
	v_mov_b32_e32 v75, v70
	v_mov_b32_e32 v78, v71
	v_mov_b32_e32 v79, v72
	v_mov_b32_e32 v145, v73
	v_mov_b32_e32 v146, v64
	v_mov_b32_e32 v149, v65
	v_mov_b32_e32 v150, v66
	v_mov_b32_e32 v152, v67
	v_permlane32_swap_b32_e32 v75, v74
	v_permlane32_swap_b32_e32 v78, v76
	v_permlane32_swap_b32_e32 v79, v77
	v_permlane32_swap_b32_e32 v145, v123
	v_permlane32_swap_b32_e32 v146, v144
	v_permlane32_swap_b32_e32 v149, v147
	v_permlane32_swap_b32_e32 v150, v148
	v_permlane32_swap_b32_e32 v152, v151
	s_cbranch_scc1 .LBB0_176
	s_add_i32 s19, s18, 8
	s_ashr_i32 s19, s19, 2
	s_add_i32 s20, s19, s31
	s_ashr_i32 s21, s20, 31
	s_lshl_b64 s[20:21], s[20:21], 19
	v_lshl_or_b32 v80, v128, 7, s20
	v_mov_b32_e32 v81, s21
	v_lshl_add_u64 v[92:93], v[112:113], 0, v[80:81]
	global_load_dwordx4 v[108:111], v[124:125], off offset:48
	global_load_dwordx4 v[104:107], v[124:125], off offset:32
	global_load_dwordx4 v[100:103], v[124:125], off offset:16
	global_load_dwordx4 v[96:99], v[124:125], off
	global_load_dwordx4 v[80:83], v[92:93], off
	global_load_dwordx4 v[84:87], v[92:93], off offset:32
	global_load_dwordx4 v[88:91], v[92:93], off offset:64
	s_nop 0
	global_load_dwordx4 v[92:95], v[92:93], off offset:96
; #define LAS __attribute__((address_space(3)))
; __device__ __forceinline__ unsigned cvtpk(float lo, float hi) { f32x2_t v = {lo, hi}; bf16x2_t b = __builtin_convertvector(v, bf16x2_t); return __builtin_bit_cast(unsigned, b); }
; #define SB_MFMA(a, b, c) __builtin_amdgcn_mfma_f32_32x32x16_bf16((a), (b), (c), 0, 0, 0)
; __device__ __forceinline__ void sw_attn(const bf16* QKV, const float* rope, const float* qg, const float* kg, const float* sinks, bf16* O, LAS unsigned char* lds, int tid) {
;     ...
;                 for (int i = 0; i < 8; ++i) { float lo_, up_; const float own = qv[0][i]; halves(own, lo_, up_); const float oth = hi ? lo_ : up_, c = i < 4 ? rraw[0][i & 3] : rraw[1][i & 3], sn = i < 4 ? rraw[2][i & 3] : rraw[3][i & 3]; qv[0][i] = own * c + oth * (hi ? sn : -sn); }
; #pragma unroll
;                 for (int ks = 0; ks < 4; ++ks) { const v4u w = {cvtpk(qv[ks][0] * QS, qv[ks][1] * QS), cvtpk(qv[ks][2] * QS, qv[ks][3] * QS), cvtpk(qv[ks][4] * QS, qv[ks][5] * QS), cvtpk(qv[ks][6] * QS, qv[ks][7] * QS)}; qf[ks] = __builtin_bit_cast(bf16x8, w); }
;             }
;             if (p < 3) SW_LOADQ(p + 1);
;             const float sink = sinks[hq] * 1.4426950408889634f;
;             f32x16 s[5]; float mx = sink;
;             const float NEG = -__builtin_inff();
; #pragma unroll
;             for (int js = 0; js < 5; ++js) {
; #pragma unroll
;                 for (int r = 0; r < 16; ++r) s[js][r] = 0.f;
;                 const bool live = !(blk == 0 && tb + js < 4);
;                 if (live) {
; #pragma unroll
;                     for (int ks = 0; ks < 4; ++ks) { const bf16x8 a = *(const LAS bf16x8*)(kl + (32 * (tb + js) + l32) * KROW + 32 * ks + 16 * hi); s[js] = SB_MFMA(a, qf[ks], s[js]); }
; #pragma unroll
;                     for (int r = 0; r < 16; ++r) {
;                         const int kk = (r & 3) + 8 * (r >> 2) + 4 * hi;
;                         float v = s[js][r];
;                         if (js == 0) v = (kk > l32) ? v : NEG;
;                         if (js == 4) v = (kk <= l32) ? v : NEG;
;                         s[js][r] = v; mx = fmaxf(mx, v);
.LBB0_176:
	v_mov_b32_e32 v69, v68
	v_pk_mul_f32 v[46:47], v[68:69], v[46:47]
	v_cndmask_b32_e64 v9, v9, -v9, s[40:41]
	s_waitcnt lgkmcnt(1)
	v_pk_mul_f32 v[46:47], v[46:47], v[20:21]
	v_pk_mul_f32 v[20:21], v[68:69], v[44:45]
	v_cndmask_b32_e64 v8, v8, -v8, s[40:41]
	v_pk_mul_f32 v[22:23], v[20:21], v[22:23]
	v_pk_mul_f32 v[20:21], v[68:69], v[42:43]
	v_cndmask_b32_e64 v11, v11, -v11, s[40:41]
	s_waitcnt lgkmcnt(0)
	v_pk_mul_f32 v[16:17], v[20:21], v[16:17]
	v_pk_mul_f32 v[20:21], v[68:69], v[40:41]
	v_cndmask_b32_e64 v10, v10, -v10, s[40:41]
	v_pk_mul_f32 v[44:45], v[20:21], v[18:19]
	v_cndmask_b32_e64 v19, v78, v76, s[40:41]
	v_cndmask_b32_e64 v18, v75, v74, s[40:41]
	v_pk_mul_f32 v[8:9], v[8:9], v[18:19]
	v_cndmask_b32_e64 v13, v13, -v13, s[40:41]
	v_pk_fma_f32 v[4:5], v[4:5], v[70:71], v[8:9]
	v_cndmask_b32_e64 v9, v145, v123, s[40:41]
	v_cndmask_b32_e64 v8, v79, v77, s[40:41]
	v_pk_mul_f32 v[8:9], v[10:11], v[8:9]
	v_cndmask_b32_e64 v12, v12, -v12, s[40:41]
	v_pk_fma_f32 v[6:7], v[6:7], v[72:73], v[8:9]
	v_cndmask_b32_e64 v9, v149, v147, s[40:41]
	v_cndmask_b32_e64 v8, v146, v144, s[40:41]
	v_pk_mul_f32 v[8:9], v[12:13], v[8:9]
	v_cndmask_b32_e64 v15, v15, -v15, s[40:41]
	v_cndmask_b32_e64 v14, v14, -v14, s[40:41]
	v_pk_fma_f32 v[0:1], v[0:1], v[64:65], v[8:9]
	v_cndmask_b32_e64 v9, v152, v151, s[40:41]
	v_cndmask_b32_e64 v8, v150, v148, s[40:41]
	v_pk_mul_f32 v[8:9], v[14:15], v[8:9]
	v_pk_mul_f32 v[62:63], v[68:69], v[62:63]
	v_pk_fma_f32 v[2:3], v[2:3], v[66:67], v[8:9]
	v_pk_mul_f32 v[0:1], v[0:1], s[74:75] op_sel_hi:[1,0]
	v_pk_mul_f32 v[36:37], v[36:37], v[62:63]
	v_pk_mul_f32 v[60:61], v[68:69], v[60:61]
	v_cvt_pk_bf16_f32 v20, v0, v1
	v_pk_mul_f32 v[0:1], v[2:3], s[74:75] op_sel_hi:[1,0]
	v_pk_mul_f32 v[38:39], v[38:39], v[60:61]
	v_pk_mul_f32 v[58:59], v[68:69], v[58:59]
	v_cvt_pk_bf16_f32 v21, v0, v1
	v_pk_mul_f32 v[0:1], v[36:37], s[74:75] op_sel_hi:[1,0]
	v_pk_mul_f32 v[32:33], v[32:33], v[58:59]
	v_pk_mul_f32 v[56:57], v[68:69], v[56:57]
	v_cvt_pk_bf16_f32 v36, v0, v1
	v_pk_mul_f32 v[0:1], v[38:39], s[74:75] op_sel_hi:[1,0]
	v_pk_mul_f32 v[34:35], v[34:35], v[56:57]
	v_pk_mul_f32 v[54:55], v[68:69], v[54:55]
	v_cvt_pk_bf16_f32 v37, v0, v1
	v_pk_mul_f32 v[0:1], v[32:33], s[74:75] op_sel_hi:[1,0]
	v_pk_mul_f32 v[28:29], v[28:29], v[54:55]
	v_pk_mul_f32 v[52:53], v[68:69], v[52:53]
	v_cvt_pk_bf16_f32 v38, v0, v1
	v_pk_mul_f32 v[0:1], v[34:35], s[74:75] op_sel_hi:[1,0]
	v_pk_mul_f32 v[30:31], v[30:31], v[52:53]
	v_pk_mul_f32 v[50:51], v[68:69], v[50:51]
	v_cvt_pk_bf16_f32 v39, v0, v1
	v_pk_mul_f32 v[0:1], v[28:29], s[74:75] op_sel_hi:[1,0]
	v_pk_mul_f32 v[24:25], v[50:51], v[24:25]
	v_pk_mul_f32 v[48:49], v[68:69], v[48:49]
	v_cvt_pk_bf16_f32 v40, v0, v1
	v_pk_mul_f32 v[0:1], v[30:31], s[74:75] op_sel_hi:[1,0]
	s_ashr_i32 s18, s18, 2
	v_pk_mul_f32 v[26:27], v[48:49], v[26:27]
	v_cvt_pk_bf16_f32 v41, v0, v1
	v_pk_mul_f32 v[0:1], v[24:25], s[74:75] op_sel_hi:[1,0]
	s_add_i32 s18, s18, s30
	v_cvt_pk_bf16_f32 v42, v0, v1
	v_pk_mul_f32 v[0:1], v[26:27], s[74:75] op_sel_hi:[1,0]
	s_ashr_i32 s19, s18, 31
	v_cvt_pk_bf16_f32 v43, v0, v1
	v_pk_mul_f32 v[0:1], v[46:47], s[74:75] op_sel_hi:[1,0]
	s_lshl_b64 s[20:21], s[18:19], 2
	v_cvt_pk_bf16_f32 v32, v0, v1
	v_pk_mul_f32 v[0:1], v[22:23], s[74:75] op_sel_hi:[1,0]
	s_add_u32 s20, s27, s20
	v_cvt_pk_bf16_f32 v33, v0, v1
	v_pk_mul_f32 v[0:1], v[16:17], s[74:75] op_sel_hi:[1,0]
	s_addc_u32 s21, s88, s21
	v_cvt_pk_bf16_f32 v34, v0, v1
	v_pk_mul_f32 v[0:1], v[44:45], s[74:75] op_sel_hi:[1,0]
	v_pk_mul_f32 v[4:5], v[4:5], s[74:75] op_sel_hi:[1,0]
	v_cvt_pk_bf16_f32 v35, v0, v1
	v_cvt_pk_bf16_f32 v18, v4, v5
	v_pk_mul_f32 v[4:5], v[6:7], s[74:75] op_sel_hi:[1,0]
	s_andn2_b64 vcc, exec, s[10:11]
	v_cvt_pk_bf16_f32 v19, v4, v5
	v_mov_b32_e32 v182, 0xff800000
	v_mov_b32_e32 v183, 0xff800000
	v_mov_b32_e32 v178, 0xff800000
	v_mov_b32_e32 v179, 0xff800000
	v_mov_b32_e32 v180, 0xff800000
	v_mov_b32_e32 v181, 0xff800000
	v_mov_b32_e32 v156, 0xff800000
	v_mov_b32_e32 v176, 0xff800000
	v_mov_b32_e32 v177, 0xff800000
	v_mov_b32_e32 v47, 0xff800000
	v_mov_b32_e32 v174, 0xff800000
	v_mov_b32_e32 v175, 0xff800000
	v_mov_b32_e32 v44, 0xff800000
	v_mov_b32_e32 v45, 0xff800000
	v_mov_b32_e32 v46, 0xff800000
	v_mov_b32_e32 v173, 0xff800000
	v_mov_b32_e32 v123, s100
	v_mul_f32_e32 v123, 0x3fb8aa3b, v123
	v_mov_b32_e32 v0, 0xff800000
	v_mov_b32_e32 v144, v123
	s_cbranch_vccnz .LBB0_178
	ds_read_b128 v[2:5], v134
	ds_read_b128 v[22:25], v134 offset:32
	s_waitcnt lgkmcnt(1)
	v_mfma_f32_32x32x16_bf16 v[2:17], v[2:5], v[18:21], 0
	s_waitcnt lgkmcnt(0)
	v_mfma_f32_32x32x16_bf16 v[2:17], v[22:25], v[36:39], v[2:17]
	ds_read_b128 v[22:25], v134 offset:64
	s_waitcnt lgkmcnt(0)
	v_mfma_f32_32x32x16_bf16 v[2:17], v[22:25], v[40:43], v[2:17]
	ds_read_b128 v[22:25], v134 offset:96
	s_waitcnt lgkmcnt(0)
	v_mfma_f32_32x32x16_bf16 v[2:17], v[22:25], v[32:35], v[2:17]
	s_nop 11
	v_cndmask_b32_e64 v182, v234, v2, s[42:43]
	v_cndmask_b32_e64 v183, v3, v234, s[44:45]
	v_cndmask_b32_e64 v178, v234, v4, s[46:47]
	v_cndmask_b32_e64 v179, v234, v5, s[48:49]
	v_max3_f32 v1, v123, v182, v183
	v_cndmask_b32_e64 v180, v234, v6, s[50:51]
	v_cndmask_b32_e64 v181, v234, v7, s[52:53]
	v_max3_f32 v1, v1, v178, v179
	v_cndmask_b32_e64 v156, v234, v8, s[54:55]
	v_cndmask_b32_e64 v176, v234, v9, s[56:57]
	v_max3_f32 v1, v1, v180, v181
	v_cndmask_b32_e64 v177, v234, v10, s[58:59]
	v_cndmask_b32_e64 v47, v234, v11, s[60:61]
	v_max3_f32 v1, v1, v156, v176
	v_cndmask_b32_e64 v174, v234, v12, s[62:63]
	v_cndmask_b32_e64 v175, v234, v13, s[64:65]
	v_max3_f32 v1, v1, v177, v47
	v_cndmask_b32_e64 v44, v234, v14, s[66:67]
	v_cndmask_b32_e64 v45, v234, v15, s[68:69]
	v_max3_f32 v1, v1, v174, v175
	v_cndmask_b32_e64 v46, v234, v16, s[70:71]
	v_max3_f32 v1, v1, v44, v45
	v_cndmask_b32_e64 v173, v234, v17, s[72:73]
	v_max3_f32 v144, v1, v46, v173
